# prompt attention fast loop: K/V tile prefetch loads via SGPR bases + 32-bit lane offsets (no 64-bit VALU pointer adds per tile)
# speedup vs baseline: 1.0065x; 1.0056x over previous
.LBB0_448:
	s_or_b64 exec, exec, s[34:35]
	s_xor_b64 s[34:35], s[20:21], -1
	s_and_b64 s[20:21], s[20:21], exec
	v_add_u32_e32 v6, 0x200, v2
	v_add_u32_e32 v14, 0x400, v2
	v_add_u32_e32 v16, 0x600, v2
	s_cselect_b32 s20, s63, s64
	v_ashrrev_i32_e32 v23, 4, v2
	v_ashrrev_i32_e32 v28, 4, v6
	v_ashrrev_i32_e32 v30, 4, v14
	v_ashrrev_i32_e32 v32, 4, v16
	s_lshl_b32 s38, s20, 7
	v_min_i32_e32 v4, 0x7f, v23
	v_min_i32_e32 v6, 0x7f, v28
	v_min_i32_e32 v14, 0x7f, v30
	v_min_i32_e32 v16, 0x7f, v32
	v_lshlrev_b32_e32 v0, 4, v2
	v_add_u32_e32 v4, s38, v4
	v_add_u32_e32 v6, s38, v6
	v_add_u32_e32 v14, s38, v14
	v_add_u32_e32 v16, s38, v16
	v_and_b32_e32 v0, 0xf0, v0
	v_ashrrev_i32_e32 v5, 31, v4
	v_ashrrev_i32_e32 v7, 31, v6
	v_ashrrev_i32_e32 v15, 31, v14
	v_ashrrev_i32_e32 v17, 31, v16
	v_lshl_add_u64 v[12:13], s[10:11], 0, v[0:1]
	v_lshlrev_b64 v[4:5], 11, v[4:5]
	v_lshlrev_b64 v[6:7], 11, v[6:7]
	v_lshlrev_b64 v[14:15], 11, v[14:15]
	v_lshlrev_b64 v[16:17], 11, v[16:17]
	v_lshl_add_u64 v[4:5], v[12:13], 0, v[4:5]
	v_lshl_add_u64 v[8:9], v[12:13], 0, v[6:7]
	v_lshl_add_u64 v[14:15], v[12:13], 0, v[14:15]
	v_lshl_add_u64 v[16:17], v[12:13], 0, v[16:17]
	global_load_dwordx4 v[4:7], v[4:5], off
	s_nop 0
	global_load_dwordx4 v[8:11], v[8:9], off
	s_nop 0
	global_load_dwordx4 v[12:15], v[14:15], off
	s_nop 0
	global_load_dwordx4 v[16:19], v[16:17], off
	v_ashrrev_i32_e32 v20, 3, v2
	v_ashrrev_i32_e32 v21, 31, v20
	v_lshlrev_b32_e32 v26, 5, v2
	s_add_i32 s20, 0, 0x11000
	v_lshlrev_b64 v[24:25], 11, v[20:21]
	v_add_u32_e32 v22, s20, v0
	v_and_b32_e32 v0, 0xe0, v26
	v_lshl_add_u64 v[24:25], s[12:13], 0, v[24:25]
	v_mad_u64_u32 v[26:27], s[20:21], v23, s51, v[22:23]
	v_lshl_add_u64 v[24:25], v[24:25], 0, v[0:1]
	v_mad_u64_u32 v[28:29], s[20:21], v28, s51, v[22:23]
	v_mad_u64_u32 v[30:31], s[20:21], v30, s51, v[22:23]
	v_mad_u64_u32 v[22:23], s[20:21], v32, s51, v[22:23]
	v_lshlrev_b32_e32 v3, 4, v3
	v_and_b32_e32 v165, 31, v2
	s_lshl_b32 s39, s65, 5
	s_ashr_i32 s40, s65, 2
	s_and_b32 s20, s39, 0x60
	v_or_b32_e32 v174, s20, v165
	s_lshl_b32 s41, s40, 7
	s_or_b32 s21, s38, 0x7f
	v_mov_b32_e32 v79, 0
	s_cmpk_lt_i32 s21, 0xffc1
	v_mov_b32_e32 v78, 0
	v_mov_b32_e32 v77, 0
	v_mov_b32_e32 v76, 0
	v_mov_b32_e32 v75, 0
	v_mov_b32_e32 v74, 0
	v_mov_b32_e32 v73, 0
	v_mov_b32_e32 v72, 0
	v_mov_b32_e32 v71, 0
	v_mov_b32_e32 v70, 0
	v_mov_b32_e32 v69, 0
	v_mov_b32_e32 v68, 0
	v_mov_b32_e32 v67, 0
	v_mov_b32_e32 v66, 0
	v_mov_b32_e32 v65, 0
	v_mov_b32_e32 v64, v79
	v_mov_b32_e32 v63, 0
	v_mov_b32_e32 v62, 0
	v_mov_b32_e32 v61, 0
	v_mov_b32_e32 v60, 0
	v_mov_b32_e32 v59, 0
	v_mov_b32_e32 v58, 0
	v_mov_b32_e32 v57, 0
	v_mov_b32_e32 v56, 0
	v_mov_b32_e32 v55, 0
	v_mov_b32_e32 v54, 0
	s_waitcnt vmcnt(3)
	ds_write_b128 v26, v[4:7]
	s_waitcnt vmcnt(2)
	ds_write_b128 v28, v[8:11]
	s_waitcnt vmcnt(1)
	ds_write_b128 v30, v[12:15]
	s_waitcnt vmcnt(0)
	ds_write_b128 v22, v[16:19]
	global_load_dwordx4 v[4:7], v[24:25], off
	global_load_dwordx4 v[8:11], v[24:25], off offset:16
	v_bfe_u32 v12, v2, 2, 4
	v_ashrrev_i32_e32 v14, 5, v2
	v_and_or_b32 v3, v3, 16, v12
	v_bfi_b32 v16, -4, v14, v2
	v_mov_b32_e32 v13, v1
	v_mul_lo_u32 v15, v20, s51
	v_lshlrev_b32_e32 v12, 12, v3
	v_lshlrev_b32_e32 v14, 3, v16
	v_add_u32_e32 v17, 0, v15
	v_lshl_add_u64 v[12:13], s[14:15], 0, v[12:13]
	v_ashrrev_i32_e32 v15, 31, v14
	v_add_u32_e32 v176, v17, v0
	v_lshl_add_u64 v[12:13], v[14:15], 1, v[12:13]
	v_bfe_u32 v0, v2, 5, 1
	v_mul_lo_u32 v2, v16, s56
	v_lshlrev_b32_e32 v3, 2, v3
	v_add_u32_e32 v2, 0, v2
	v_add_u32_e32 v177, v2, v3
	v_add_u32_e32 v178, 0x8800, v177
	v_lshl_add_u64 v[166:167], v[24:25], 0, s[4:5]
	v_lshlrev_b32_e32 v173, 4, v0
	v_lshlrev_b32_e32 v164, 3, v0
	v_mov_b32_e32 v53, 0
	v_mov_b32_e32 v52, 0
	v_mov_b32_e32 v51, 0
	v_mov_b32_e32 v50, 0
	v_mov_b32_e32 v49, 0
	v_mov_b32_e32 v48, v79
	v_mov_b32_e32 v47, 0
	v_mov_b32_e32 v46, 0
	v_mov_b32_e32 v45, 0
	v_mov_b32_e32 v44, 0
	v_mov_b32_e32 v43, 0
	v_mov_b32_e32 v42, 0
	v_mov_b32_e32 v41, 0
	v_mov_b32_e32 v40, 0
	v_mov_b32_e32 v39, 0
	v_mov_b32_e32 v38, 0
	v_mov_b32_e32 v37, 0
	v_mov_b32_e32 v36, 0
	v_mov_b32_e32 v35, 0
	v_mov_b32_e32 v34, 0
	v_mov_b32_e32 v33, 0
	v_mov_b32_e32 v32, v79
	v_mov_b32_e32 v31, 0
	v_mov_b32_e32 v30, 0
	v_mov_b32_e32 v29, 0
	v_mov_b32_e32 v28, 0
	v_mov_b32_e32 v27, 0
	v_mov_b32_e32 v26, 0
	v_mov_b32_e32 v25, 0
	s_waitcnt vmcnt(1)
	ds_write_b128 v176, v[4:7]
	s_waitcnt vmcnt(0)
	ds_write_b128 v176, v[8:11] offset:16
	global_load_dwordx4 v[4:7], v[12:13], off
	global_load_dwordx4 v[8:11], v[12:13], off offset:2048
	v_lshl_add_u64 v[168:169], v[12:13], 0, s[4:5]
	v_mov_b32_e32 v24, 0
	v_mov_b32_e32 v23, 0
	v_mov_b32_e32 v22, 0
	v_mov_b32_e32 v21, 0
	v_mov_b32_e32 v20, 0
	v_mov_b32_e32 v19, 0
	v_mov_b32_e32 v18, 0
	v_mov_b32_e32 v17, 0
	v_mov_b32_e32 v16, v79
	v_mov_b32_e32 v175, 0
	s_waitcnt vmcnt(1)
	v_and_b32_e32 v2, 0xffff, v4
	v_lshrrev_b32_e32 v3, 16, v4
	v_and_b32_e32 v4, 0xffff, v5
	v_lshrrev_b32_e32 v5, 16, v5
	v_and_b32_e32 v12, 0xffff, v6
	v_lshrrev_b32_e32 v6, 16, v6
	v_and_b32_e32 v13, 0xffff, v7
	v_lshrrev_b32_e32 v7, 16, v7
	s_waitcnt vmcnt(0)
	v_lshl_or_b32 v2, v8, 16, v2
	v_and_or_b32 v3, v8, s57, v3
	v_lshl_or_b32 v4, v9, 16, v4
	v_and_or_b32 v5, v9, s57, v5
	v_lshl_or_b32 v8, v10, 16, v12
	v_and_or_b32 v6, v10, s57, v6
	v_lshl_or_b32 v9, v11, 16, v13
	v_and_or_b32 v7, v11, s57, v7
	ds_write2_b32 v178, v2, v3 offset1:34
	ds_write2_b32 v178, v4, v5 offset0:68 offset1:102
	ds_write2_b32 v178, v8, v6 offset0:136 offset1:170
	ds_write2_b32 v178, v9, v7 offset0:204 offset1:238
	global_load_dwordx4 v[120:123], v[166:167], off offset:16
	global_load_dwordx4 v[124:127], v[166:167], off
	global_load_dwordx4 v[116:119], v[168:169], off
	global_load_dwordx4 v[112:115], v[168:169], off offset:2048
	v_mul_u32_u24_e32 v2, 0x110, v174
	v_or_b32_e32 v3, s41, v173
	v_add3_u32 v179, v3, v2, s50
	v_mul_u32_u24_e32 v2, 0x88, v165
	v_mul_u32_u24_e32 v3, 0x110, v165
	v_add3_u32 v2, v2, v164, s58
	v_add3_u32 v180, v173, v3, s41
	s_waitcnt lgkmcnt(0)
	s_barrier
	s_cbranch_scc1 .LBB0_465
	s_ashr_i32 s41, s21, 31
	v_lshlrev_b32_e32 v0, 2, v0
	s_lshr_b32 s41, s41, 26
	v_sub_u32_e32 v0, v0, v165
	s_add_i32 s21, s21, s41
	v_subrev_u32_e32 v0, s20, v0
	v_mov_b32_e32 v14, v1
	v_mov_b32_e32 v15, v1
	s_ashr_i32 s21, s21, 6
	s_or_b32 s42, s20, s38
	v_add_u32_e32 v181, 0, v2
	v_subrev_u32_e32 v182, s38, v0
	v_mov_b32_e32 v0, v1
	v_mov_b32_e32 v2, v1
	v_mov_b32_e32 v3, v1
	v_mov_b32_e32 v4, v1
	v_mov_b32_e32 v5, v1
	v_mov_b32_e32 v6, v1
	v_mov_b32_e32 v7, v1
	v_mov_b32_e32 v8, v1
	v_mov_b32_e32 v9, v1
	v_mov_b32_e32 v10, v1
	v_mov_b32_e32 v11, v1
	v_mov_b32_e32 v12, v1
	v_mov_b32_e32 v13, v1
	v_mov_b64_e32 v[30:31], v[14:15]
	v_mov_b64_e32 v[46:47], v[14:15]
	v_mov_b64_e32 v[62:63], v[14:15]
	v_mov_b64_e32 v[78:79], v[14:15]
	s_min_i32 s41, s21, 0xff
	s_ashr_i32 s43, s42, 6
	s_mov_b32 s44, 0
	v_mov_b32_e32 v175, 0
	s_movk_i32 s45, 0xda
	v_mov_b64_e32 v[28:29], v[12:13]
	v_mov_b64_e32 v[26:27], v[10:11]
	v_mov_b64_e32 v[24:25], v[8:9]
	v_mov_b64_e32 v[22:23], v[6:7]
	v_mov_b64_e32 v[20:21], v[4:5]
	v_mov_b64_e32 v[18:19], v[2:3]
	v_mov_b64_e32 v[16:17], v[0:1]
	v_mov_b64_e32 v[44:45], v[12:13]
	v_mov_b64_e32 v[42:43], v[10:11]
	v_mov_b64_e32 v[40:41], v[8:9]
	v_mov_b64_e32 v[38:39], v[6:7]
	v_mov_b64_e32 v[36:37], v[4:5]
	v_mov_b64_e32 v[34:35], v[2:3]
	v_mov_b64_e32 v[32:33], v[0:1]
	v_mov_b64_e32 v[60:61], v[12:13]
	v_mov_b64_e32 v[58:59], v[10:11]
	v_mov_b64_e32 v[56:57], v[8:9]
	v_mov_b64_e32 v[54:55], v[6:7]
	v_mov_b64_e32 v[52:53], v[4:5]
	v_mov_b64_e32 v[50:51], v[2:3]
	v_mov_b64_e32 v[48:49], v[0:1]
	v_mov_b64_e32 v[76:77], v[12:13]
	v_mov_b64_e32 v[74:75], v[10:11]
	v_mov_b64_e32 v[72:73], v[8:9]
	v_mov_b64_e32 v[70:71], v[6:7]
	v_mov_b64_e32 v[68:69], v[4:5]
	v_mov_b64_e32 v[66:67], v[2:3]
	v_mov_b64_e32 v[64:65], v[0:1]
	v_cmp_gt_f32_e32 vcc, 0xc2700000, v171
	s_cbranch_vccnz .LBB0_451
	s_mov_b32 s100, 0x05040100
	s_mov_b32 s101, 0x07060302
	ds_read_b128 v[234:237], v179
	ds_read_b128 v[238:241], v179 offset:32
	ds_read_b128 v[244:247], v179 offset:64
	ds_read_b128 v[248:251], v179 offset:96
	s_waitcnt lgkmcnt(0)
	v_readfirstlane_b32 s86, v166
	v_readfirstlane_b32 s87, v167
	v_readfirstlane_b32 s88, v168
	v_readfirstlane_b32 s89, v169
	v_subrev_u32_e32 v252, s86, v166
	v_subrev_u32_e32 v253, s88, v168
	s_branch .Lqf_451

.Lqf_451:
	s_add_u32 s86, s86, s4
	s_addc_u32 s87, s87, s5
	s_add_u32 s88, s88, s4
	s_addc_u32 s89, s89, s5
	global_load_dwordx4 v[10:13], v252, s[86:87] offset:16
	global_load_dwordx4 v[128:131], v252, s[86:87]
	global_load_dwordx4 v[2:5], v253, s[88:89]
	global_load_dwordx4 v[6:9], v253, s[88:89] offset:2048
	s_cmp_le_i32 s44, s43
	s_cselect_b64 s[20:21], -1, 0
	s_cmp_gt_i32 s44, s43
	s_cbranch_scc1 .Lqf_455
	ds_read_b128 v[80:83], v180
	ds_read_b128 v[136:139], v180 offset:32
	ds_read_b128 v[100:103], v180 offset:8704
	ds_read_b128 v[140:143], v180 offset:8736
	s_sub_i32 s68, s45, 64
	s_cmp_le_i32 s68, s42
	s_waitcnt lgkmcnt(3)
	v_mfma_f32_32x32x16_bf16 v[80:95], v[80:83], v[234:237], 0
	s_waitcnt lgkmcnt(1)
	v_mfma_f32_32x32x16_bf16 v[96:111], v[100:103], v[234:237], 0
	s_waitcnt lgkmcnt(2)
	v_mfma_f32_32x32x16_bf16 v[80:95], v[136:139], v[238:241], v[80:95]
	s_waitcnt lgkmcnt(0)
	v_mfma_f32_32x32x16_bf16 v[96:111], v[140:143], v[238:241], v[96:111]
	ds_read_b128 v[132:135], v180 offset:64
	ds_read_b128 v[144:147], v180 offset:96
	s_waitcnt lgkmcnt(1)
	v_mfma_f32_32x32x16_bf16 v[80:95], v[132:135], v[244:247], v[80:95]
	ds_read_b128 v[132:135], v180 offset:8768
	ds_read_b128 v[184:187], v180 offset:8800
	s_waitcnt lgkmcnt(1)
	v_mfma_f32_32x32x16_bf16 v[96:111], v[132:135], v[244:247], v[96:111]
	s_waitcnt lgkmcnt(2)
	v_mfma_f32_32x32x16_bf16 v[80:95], v[144:147], v[248:251], v[80:95]
	s_waitcnt lgkmcnt(0)
	v_mfma_f32_32x32x16_bf16 v[96:111], v[184:187], v[248:251], v[96:111]
	s_cbranch_scc1 .Lqf_454
	v_add_u32_e32 v0, s45, v182
	v_add_u32_e32 v134, 0xffffff27, v0
	s_add_i32 s68, 0, 0x19800
	v_max_i32_e32 v134, 0xffffff80, v134
	v_lshl_add_u32 v136, v134, 2, s68
	v_add_u32_e32 v134, 0xffffff28, v0
	v_add_u32_e32 v132, 0xffffff26, v0
	v_add_u32_e32 v133, 0xffffff46, v0
	v_add_u32_e32 v135, 0xffffff47, v0
	v_add_u32_e32 v137, 0xffffff48, v0
	v_max_i32_e32 v134, 0xffffff80, v134
	v_add_u32_e32 v139, 0xffffff49, v0
	v_max_i32_e32 v132, 0xffffff80, v132
	v_max_i32_e32 v133, 0xffffff80, v133
	v_max_i32_e32 v135, 0xffffff80, v135
	v_max_i32_e32 v137, 0xffffff80, v137
	v_lshl_add_u32 v138, v134, 2, s68
	v_add_u32_e32 v134, 0xffffff29, v0
	v_max_i32_e32 v139, 0xffffff80, v139
	v_lshl_add_u32 v132, v132, 2, s68
	v_lshl_add_u32 v133, v133, 2, s68
	v_lshl_add_u32 v135, v135, 2, s68
	v_lshl_add_u32 v137, v137, 2, s68
	v_max_i32_e32 v134, 0xffffff80, v134
	v_lshl_add_u32 v139, v139, 2, s68
	v_lshl_add_u32 v140, v134, 2, s68
	ds_read_b32 v132, v132 offset:512
	ds_read_b32 v134, v133 offset:512
	ds_read_b32 v133, v136 offset:512
	ds_read_b32 v135, v135 offset:512
	ds_read_b32 v136, v138 offset:512
	ds_read_b32 v138, v137 offset:512
	ds_read_b32 v137, v140 offset:512
	ds_read_b32 v139, v139 offset:512
	v_add_u32_e32 v142, 0xffffff2f, v0
	v_max_i32_e32 v142, 0xffffff80, v142
	v_lshl_add_u32 v144, v142, 2, s68
	v_add_u32_e32 v142, 0xffffff30, v0
	v_add_u32_e32 v140, 0xffffff2e, v0
	v_add_u32_e32 v141, 0xffffff4e, v0
	v_add_u32_e32 v143, 0xffffff4f, v0
	v_add_u32_e32 v145, 0xffffff50, v0
	v_max_i32_e32 v142, 0xffffff80, v142
	v_add_u32_e32 v147, 0xffffff51, v0
	v_max_i32_e32 v140, 0xffffff80, v140
	v_max_i32_e32 v141, 0xffffff80, v141
	v_max_i32_e32 v143, 0xffffff80, v143
	v_max_i32_e32 v145, 0xffffff80, v145
	v_lshl_add_u32 v146, v142, 2, s68
	v_add_u32_e32 v142, 0xffffff31, v0
	v_max_i32_e32 v147, 0xffffff80, v147
	v_lshl_add_u32 v140, v140, 2, s68
	v_lshl_add_u32 v141, v141, 2, s68
	v_lshl_add_u32 v143, v143, 2, s68
	v_lshl_add_u32 v145, v145, 2, s68
	v_max_i32_e32 v142, 0xffffff80, v142
	v_lshl_add_u32 v147, v147, 2, s68
	v_lshl_add_u32 v168, v142, 2, s68
	ds_read_b32 v140, v140 offset:512
	ds_read_b32 v142, v141 offset:512
	ds_read_b32 v141, v144 offset:512
	ds_read_b32 v143, v143 offset:512
	ds_read_b32 v144, v146 offset:512
	ds_read_b32 v146, v145 offset:512
	ds_read_b32 v145, v168 offset:512
	ds_read_b32 v147, v147 offset:512
	v_add_u32_e32 v184, 0xffffff57, v0
	v_max_i32_e32 v184, 0xffffff80, v184
	v_lshl_add_u32 v185, v184, 2, s68
	v_add_u32_e32 v184, 0xffffff38, v0
	v_add_u32_e32 v186, 0xffffff58, v0
	v_max_i32_e32 v184, 0xffffff80, v184
	v_add_u32_e32 v168, 0xffffff36, v0
	v_add_u32_e32 v169, 0xffffff56, v0
	v_max_i32_e32 v186, 0xffffff80, v186
	v_lshl_add_u32 v187, v184, 2, s68
	v_add_u32_e32 v184, 0xffffff39, v0
	v_max_i32_e32 v168, 0xffffff80, v168
	v_max_i32_e32 v169, 0xffffff80, v169
	v_add_u32_e32 v183, 0xffffff37, v0
	v_lshl_add_u32 v188, v186, 2, s68
	v_add_u32_e32 v186, 0xffffff59, v0
	v_max_i32_e32 v184, 0xffffff80, v184
	v_lshl_add_u32 v168, v168, 2, s68
	v_lshl_add_u32 v169, v169, 2, s68
	v_max_i32_e32 v183, 0xffffff80, v183
	v_max_i32_e32 v186, 0xffffff80, v186
	v_lshl_add_u32 v189, v184, 2, s68
	v_lshl_add_u32 v183, v183, 2, s68
	v_lshl_add_u32 v190, v186, 2, s68
	ds_read_b32 v168, v168 offset:512
	ds_read_b32 v184, v169 offset:512
	ds_read_b32 v169, v183 offset:512
	ds_read_b32 v185, v185 offset:512
	ds_read_b32 v186, v187 offset:512
	ds_read_b32 v188, v188 offset:512
	ds_read_b32 v187, v189 offset:512
	ds_read_b32 v189, v190 offset:512
	v_add_u32_e32 v183, 0xffffff3e, v0
	v_add_u32_e32 v190, 0xffffff5e, v0
	v_max_i32_e32 v183, 0xffffff80, v183
	v_add_u32_e32 v191, 0xffffff3f, v0
	v_add_u32_e32 v192, 0xffffff5f, v0
	v_add_u32_e32 v193, 0xffffff40, v0
	v_add_u32_e32 v196, 0xffffff60, v0
	v_add_u32_e32 v197, 0xffffff41, v0
	v_add_u32_e32 v0, 0xffffff61, v0
	v_max_i32_e32 v190, 0xffffff80, v190
	v_lshl_add_u32 v183, v183, 2, s68
	v_max_i32_e32 v191, 0xffffff80, v191
	v_max_i32_e32 v192, 0xffffff80, v192
	v_max_i32_e32 v193, 0xffffff80, v193
	v_max_i32_e32 v196, 0xffffff80, v196
	v_max_i32_e32 v197, 0xffffff80, v197
	v_max_i32_e32 v0, 0xffffff80, v0
	v_lshl_add_u32 v190, v190, 2, s68
	v_lshl_add_u32 v191, v191, 2, s68
	v_lshl_add_u32 v192, v192, 2, s68
	v_lshl_add_u32 v193, v193, 2, s68
	v_lshl_add_u32 v196, v196, 2, s68
	v_lshl_add_u32 v197, v197, 2, s68
	s_waitcnt lgkmcnt(14)
	v_pk_add_f32 v[82:83], v[82:83], v[136:137]
	v_pk_add_f32 v[80:81], v[80:81], v[132:133]
	s_waitcnt lgkmcnt(9)
	v_pk_add_f32 v[86:87], v[86:87], v[144:145]
	v_pk_add_f32 v[84:85], v[84:85], v[140:141]
	v_lshl_add_u32 v0, v0, 2, s68
	ds_read_b32 v132, v183 offset:512
	ds_read_b32 v136, v190 offset:512
	ds_read_b32 v140, v193 offset:512
	ds_read_b32 v141, v197 offset:512
	ds_read_b32 v133, v191 offset:512
	ds_read_b32 v137, v192 offset:512
	ds_read_b32 v144, v196 offset:512
	ds_read_b32 v145, v0 offset:512
	s_waitcnt lgkmcnt(9)
	v_pk_add_f32 v[90:91], v[90:91], v[186:187]
	v_pk_add_f32 v[88:89], v[88:89], v[168:169]
	s_waitcnt lgkmcnt(4)
	v_pk_add_f32 v[94:95], v[94:95], v[140:141]
	s_waitcnt lgkmcnt(3)
	v_pk_add_f32 v[92:93], v[92:93], v[132:133]
	v_pk_add_f32 v[98:99], v[98:99], v[138:139]
	v_pk_add_f32 v[96:97], v[96:97], v[134:135]
	v_pk_add_f32 v[102:103], v[102:103], v[146:147]
	v_pk_add_f32 v[100:101], v[100:101], v[142:143]
	v_pk_add_f32 v[106:107], v[106:107], v[188:189]
	v_pk_add_f32 v[104:105], v[104:105], v[184:185]
	s_waitcnt lgkmcnt(0)
	v_pk_add_f32 v[110:111], v[110:111], v[144:145]
	v_pk_add_f32 v[108:109], v[108:109], v[136:137]

.Lqf_457:
	s_waitcnt vmcnt(5)
	s_waitcnt vmcnt(4)
	v_perm_b32 v0, v112, v116, s100
	v_perm_b32 v80, v112, v116, s101
	v_add_u32_e32 v81, 0xcc00, v177
	ds_write2_b32 v81, v0, v80 offset1:34
	v_perm_b32 v0, v113, v117, s100
	v_perm_b32 v80, v113, v117, s101
	ds_write2_b32 v81, v0, v80 offset0:68 offset1:102
	v_perm_b32 v0, v114, v118, s100
	v_perm_b32 v80, v114, v118, s101
	ds_write2_b32 v81, v0, v80 offset0:136 offset1:170
	v_perm_b32 v0, v115, v119, s100
	v_perm_b32 v80, v115, v119, s101
	s_mov_b64 s[20:21], -1
	s_cmp_ge_i32 s44, s41
	v_readfirstlane_b32 s69, v0
	v_readfirstlane_b32 s68, v0
	ds_write2_b32 v81, v0, v80 offset0:204 offset1:238
	s_waitcnt lgkmcnt(0)
	s_barrier
	s_cbranch_scc1 .Lqf_450
	s_add_u32 s86, s86, s4
	s_addc_u32 s87, s87, s5
	s_add_u32 s88, s88, s4
	s_addc_u32 s89, s89, s5
	global_load_dwordx4 v[120:123], v252, s[86:87] offset:16
	global_load_dwordx4 v[124:127], v252, s[86:87]
	global_load_dwordx4 v[116:119], v253, s[88:89]
	global_load_dwordx4 v[112:115], v253, s[88:89] offset:2048
	s_cmp_lt_i32 s44, s43
	s_cselect_b64 s[20:21], -1, 0
	s_cmp_ge_i32 s44, s43
	s_cbranch_scc1 .Lqf_462
	ds_read_b128 v[80:83], v180 offset:17408
	ds_read_b128 v[152:155], v180 offset:17440
	ds_read_b128 v[100:103], v180 offset:26112
	ds_read_b128 v[156:159], v180 offset:26144
	s_cmp_le_i32 s45, s42
	s_waitcnt lgkmcnt(3)
	v_mfma_f32_32x32x16_bf16 v[80:95], v[80:83], v[234:237], 0
	s_waitcnt lgkmcnt(1)
	v_mfma_f32_32x32x16_bf16 v[96:111], v[100:103], v[234:237], 0
	s_waitcnt lgkmcnt(2)
	v_mfma_f32_32x32x16_bf16 v[80:95], v[152:155], v[238:241], v[80:95]
	s_waitcnt lgkmcnt(0)
	v_mfma_f32_32x32x16_bf16 v[96:111], v[156:159], v[238:241], v[96:111]
	ds_read_b128 v[148:151], v180 offset:17472
	ds_read_b128 v[160:163], v180 offset:17504
	s_waitcnt lgkmcnt(1)
	v_mfma_f32_32x32x16_bf16 v[80:95], v[148:151], v[244:247], v[80:95]
	ds_read_b128 v[148:151], v180 offset:26176
	ds_read_b128 v[184:187], v180 offset:26208
	s_waitcnt lgkmcnt(1)
	v_mfma_f32_32x32x16_bf16 v[96:111], v[148:151], v[244:247], v[96:111]
	s_waitcnt lgkmcnt(2)
	v_mfma_f32_32x32x16_bf16 v[80:95], v[160:163], v[248:251], v[80:95]
	s_waitcnt lgkmcnt(0)
	v_mfma_f32_32x32x16_bf16 v[96:111], v[184:187], v[248:251], v[96:111]
	s_cbranch_scc1 .Lqf_461
	v_add_u32_e32 v0, s45, v182
	v_add_u32_e32 v148, 0xffffff67, v0
	s_add_i32 s68, 0, 0x19800
	v_max_i32_e32 v148, 0xffffff80, v148
	v_lshl_add_u32 v150, v148, 2, s68
	v_add_u32_e32 v148, 0xffffff68, v0
	v_add_u32_e32 v14, 0xffffff66, v0
	v_add_u32_e32 v15, 0xffffff86, v0
	v_add_u32_e32 v149, 0xffffff87, v0
	v_add_u32_e32 v151, 0xffffff88, v0
	v_max_i32_e32 v148, 0xffffff80, v148
	v_add_u32_e32 v153, 0xffffff89, v0
	v_max_i32_e32 v14, 0xffffff80, v14
	v_max_i32_e32 v15, 0xffffff80, v15
	v_max_i32_e32 v149, 0xffffff80, v149
	v_max_i32_e32 v151, 0xffffff80, v151
	v_lshl_add_u32 v152, v148, 2, s68
	v_add_u32_e32 v148, 0xffffff69, v0
	v_max_i32_e32 v153, 0xffffff80, v153
	v_lshl_add_u32 v14, v14, 2, s68
	v_lshl_add_u32 v15, v15, 2, s68
	v_lshl_add_u32 v149, v149, 2, s68
	v_lshl_add_u32 v151, v151, 2, s68
	v_max_i32_e32 v148, 0xffffff80, v148
	v_lshl_add_u32 v153, v153, 2, s68
	v_lshl_add_u32 v154, v148, 2, s68
	ds_read_b32 v14, v14 offset:512
	ds_read_b32 v148, v15 offset:512
	ds_read_b32 v15, v150 offset:512
	ds_read_b32 v149, v149 offset:512
	ds_read_b32 v150, v152 offset:512
	ds_read_b32 v152, v151 offset:512
	ds_read_b32 v151, v154 offset:512
	ds_read_b32 v153, v153 offset:512
	v_add_u32_e32 v156, 0xffffff6f, v0
	v_max_i32_e32 v156, 0xffffff80, v156
	v_lshl_add_u32 v158, v156, 2, s68
	v_add_u32_e32 v156, 0xffffff70, v0
	v_add_u32_e32 v154, 0xffffff6e, v0
	v_add_u32_e32 v155, 0xffffff8e, v0
	v_add_u32_e32 v157, 0xffffff8f, v0
	v_add_u32_e32 v159, 0xffffff90, v0
	v_max_i32_e32 v156, 0xffffff80, v156
	v_add_u32_e32 v161, 0xffffff91, v0
	v_max_i32_e32 v154, 0xffffff80, v154
	v_max_i32_e32 v155, 0xffffff80, v155
	v_max_i32_e32 v157, 0xffffff80, v157
	v_max_i32_e32 v159, 0xffffff80, v159
	v_lshl_add_u32 v160, v156, 2, s68
	v_add_u32_e32 v156, 0xffffff71, v0
	v_max_i32_e32 v161, 0xffffff80, v161
	v_lshl_add_u32 v154, v154, 2, s68
	v_lshl_add_u32 v155, v155, 2, s68
	v_lshl_add_u32 v157, v157, 2, s68
	v_lshl_add_u32 v159, v159, 2, s68
	v_max_i32_e32 v156, 0xffffff80, v156
	v_lshl_add_u32 v161, v161, 2, s68
	v_lshl_add_u32 v162, v156, 2, s68
	ds_read_b32 v154, v154 offset:512
	ds_read_b32 v156, v155 offset:512
	ds_read_b32 v155, v158 offset:512
	ds_read_b32 v157, v157 offset:512
	ds_read_b32 v158, v160 offset:512
	ds_read_b32 v160, v159 offset:512
	ds_read_b32 v159, v162 offset:512
	ds_read_b32 v161, v161 offset:512
	v_add_u32_e32 v184, 0xffffff97, v0
	v_max_i32_e32 v184, 0xffffff80, v184
	v_lshl_add_u32 v185, v184, 2, s68
	v_add_u32_e32 v184, 0xffffff78, v0
	v_add_u32_e32 v186, 0xffffff98, v0
	v_max_i32_e32 v184, 0xffffff80, v184
	v_add_u32_e32 v162, 0xffffff76, v0
	v_add_u32_e32 v163, 0xffffff96, v0
	v_max_i32_e32 v186, 0xffffff80, v186
	v_lshl_add_u32 v187, v184, 2, s68
	v_add_u32_e32 v184, 0xffffff79, v0
	v_max_i32_e32 v162, 0xffffff80, v162
	v_max_i32_e32 v163, 0xffffff80, v163
	v_add_u32_e32 v183, 0xffffff77, v0
	v_lshl_add_u32 v188, v186, 2, s68
	v_add_u32_e32 v186, 0xffffff99, v0
	v_max_i32_e32 v184, 0xffffff80, v184
	v_lshl_add_u32 v162, v162, 2, s68
	v_lshl_add_u32 v163, v163, 2, s68
	v_max_i32_e32 v183, 0xffffff80, v183
	v_max_i32_e32 v186, 0xffffff80, v186
	v_lshl_add_u32 v189, v184, 2, s68
	v_lshl_add_u32 v183, v183, 2, s68
	v_lshl_add_u32 v190, v186, 2, s68
	ds_read_b32 v162, v162 offset:512
	ds_read_b32 v184, v163 offset:512
	ds_read_b32 v163, v183 offset:512
	ds_read_b32 v185, v185 offset:512
	ds_read_b32 v186, v187 offset:512
	ds_read_b32 v188, v188 offset:512
	ds_read_b32 v187, v189 offset:512
	ds_read_b32 v189, v190 offset:512
	v_add_u32_e32 v183, 0xffffff7e, v0
	v_add_u32_e32 v190, 0xffffff9e, v0
	v_max_i32_e32 v183, 0xffffff80, v183
	v_add_u32_e32 v191, 0xffffff7f, v0
	v_add_u32_e32 v192, 0xffffff9f, v0
	v_add_u32_e32 v193, 0xffffff80, v0
	v_add_u32_e32 v196, 0xffffffa0, v0
	v_add_u32_e32 v197, 0xffffff81, v0
	v_add_u32_e32 v0, 0xffffffa1, v0
	v_max_i32_e32 v190, 0xffffff80, v190
	v_lshl_add_u32 v183, v183, 2, s68
	v_max_i32_e32 v191, 0xffffff80, v191
	v_max_i32_e32 v192, 0xffffff80, v192
	v_max_i32_e32 v193, 0xffffff80, v193
	v_max_i32_e32 v196, 0xffffff80, v196
	v_max_i32_e32 v197, 0xffffff80, v197
	v_max_i32_e32 v0, 0xffffff80, v0
	v_lshl_add_u32 v190, v190, 2, s68
	v_lshl_add_u32 v191, v191, 2, s68
	v_lshl_add_u32 v192, v192, 2, s68
	v_lshl_add_u32 v193, v193, 2, s68
	v_lshl_add_u32 v196, v196, 2, s68
	v_lshl_add_u32 v197, v197, 2, s68
	s_waitcnt lgkmcnt(14)
	v_pk_add_f32 v[82:83], v[82:83], v[150:151]
	v_pk_add_f32 v[80:81], v[80:81], v[14:15]
	s_waitcnt lgkmcnt(9)
	v_pk_add_f32 v[86:87], v[86:87], v[158:159]
	v_pk_add_f32 v[84:85], v[84:85], v[154:155]
	v_lshl_add_u32 v0, v0, 2, s68
	ds_read_b32 v14, v183 offset:512
	ds_read_b32 v150, v190 offset:512
	ds_read_b32 v154, v193 offset:512
	ds_read_b32 v155, v197 offset:512
	ds_read_b32 v15, v191 offset:512
	ds_read_b32 v151, v192 offset:512
	ds_read_b32 v158, v196 offset:512
	ds_read_b32 v159, v0 offset:512
	s_waitcnt lgkmcnt(9)
	v_pk_add_f32 v[90:91], v[90:91], v[186:187]
	v_pk_add_f32 v[88:89], v[88:89], v[162:163]
	s_waitcnt lgkmcnt(4)
	v_pk_add_f32 v[94:95], v[94:95], v[154:155]
	s_waitcnt lgkmcnt(3)
	v_pk_add_f32 v[92:93], v[92:93], v[14:15]
	v_pk_add_f32 v[98:99], v[98:99], v[152:153]
	v_pk_add_f32 v[96:97], v[96:97], v[148:149]
	v_pk_add_f32 v[102:103], v[102:103], v[160:161]
	v_pk_add_f32 v[100:101], v[100:101], v[156:157]
	v_pk_add_f32 v[106:107], v[106:107], v[188:189]
	v_pk_add_f32 v[104:105], v[104:105], v[184:185]
	s_waitcnt lgkmcnt(0)
	v_pk_add_f32 v[110:111], v[110:111], v[158:159]
	v_pk_add_f32 v[108:109], v[108:109], v[150:151]
